# seams: flat top level (XCD-last adds to the top counter without waiting, everyone polls the counter), replaces the two generation words
# speedup vs baseline: 1.0037x; 1.0037x over previous
.LBB0_73:
	s_or_b64 exec, exec, s[10:11]
	v_cvt_f32_u32_e32 v6, v4
	s_waitcnt vmcnt(0)
	v_readfirstlane_b32 s8, v5
	v_sub_u32_e32 v5, 0, v4
	v_rcp_iflag_f32_e32 v6, v6
	v_add_u32_e32 v7, s8, v3
	v_mul_f32_e32 v6, 0x4f7ffffe, v6
	v_cvt_u32_f32_e32 v6, v6
	v_mul_lo_u32 v3, v5, v6
	v_mul_hi_u32 v3, v6, v3
	v_add_u32_e32 v3, v6, v3
	v_mul_hi_u32 v3, v7, v3
	v_mul_lo_u32 v5, v3, v4
	v_sub_u32_e32 v5, v7, v5
	v_add_u32_e32 v6, 1, v3
	v_cmp_ge_u32_e32 vcc, v5, v4
	s_nop 1
	v_cndmask_b32_e32 v3, v3, v6, vcc
	v_sub_u32_e32 v6, v5, v4
	v_cndmask_b32_e32 v5, v5, v6, vcc
	v_add_u32_e32 v6, 1, v3
	v_cmp_ge_u32_e32 vcc, v5, v4
	v_add_u32_e32 v5, 1, v7
	s_nop 0
	v_cndmask_b32_e32 v3, v3, v6, vcc
	v_mul_lo_u32 v6, v4, v3
	v_add_u32_e32 v4, v6, v4
	v_cmp_ne_u32_e32 vcc, v5, v4
	s_cbranch_vccnz .Lsm0_poll
	buffer_wbl2 sc1
	s_waitcnt vmcnt(0) lgkmcnt(0)
	v_mov_b32_e32 v5, 0x1e03000
	v_mov_b32_e32 v6, 1
	global_atomic_add v5, v6, s[40:41] offset:1024
.Lsm0_poll:
	s_waitcnt lgkmcnt(0)
	v_add_u32_e32 v6, 1, v3
	v_mul_lo_u32 v6, v6, v2
	s_add_u32 s98, s40, 0x1e03400
	s_addc_u32 s99, s41, 0
	v_mov_b32_e32 v7, 0
	s_mov_b32 s101, 0x800
.Lsm0_loop:
	global_load_dword v5, v7, s[98:99] sc1
	s_waitcnt vmcnt(0)
	v_cmp_ge_u32_e32 vcc, v5, v6
	s_cbranch_vccnz .Lsm0_done
	s_sleep 1
	s_add_i32 s101, s101, -1
	s_cmp_lg_u32 s101, 0
	s_cbranch_scc1 .Lsm0_loop
.Lsm0_done:
	buffer_inv sc1
	s_waitcnt vmcnt(0)
.LBB0_107:
	s_or_b64 exec, exec, s[0:1]
	s_waitcnt lgkmcnt(0)
	s_barrier

.Lsm1_done:
	buffer_inv sc1
	s_waitcnt vmcnt(0)
.LBB0_264:
	s_or_b64 exec, exec, s[0:1]
	s_waitcnt lgkmcnt(0)
	s_barrier

.Lsm2_done:
	buffer_inv sc1
	s_waitcnt vmcnt(0)
.LBB0_346:
	s_or_b64 exec, exec, s[4:5]
	s_waitcnt lgkmcnt(0)
	s_barrier

.Lsm3_done:
	buffer_inv sc1
	s_waitcnt vmcnt(0)
.LBB0_421:
	s_or_b64 exec, exec, s[4:5]
	s_waitcnt lgkmcnt(0)
	s_barrier

.Lsm4_done:
	buffer_inv sc1
	s_waitcnt vmcnt(0)
.LBB0_743:
	s_or_b64 exec, exec, s[0:1]
	s_waitcnt lgkmcnt(0)
	s_barrier

.LBB0_864:
	s_or_b64 exec, exec, s[8:9]
	v_cvt_f32_u32_e32 v6, v4
	s_waitcnt vmcnt(0)
	v_readfirstlane_b32 s6, v5
	v_sub_u32_e32 v5, 0, v4
	v_rcp_iflag_f32_e32 v6, v6
	v_add_u32_e32 v7, s6, v3
	v_mul_f32_e32 v6, 0x4f7ffffe, v6
	v_cvt_u32_f32_e32 v6, v6
	v_mul_lo_u32 v3, v5, v6
	v_mul_hi_u32 v3, v6, v3
	v_add_u32_e32 v3, v6, v3
	v_mul_hi_u32 v3, v7, v3
	v_mul_lo_u32 v5, v3, v4
	v_sub_u32_e32 v5, v7, v5
	v_add_u32_e32 v6, 1, v3
	v_cmp_ge_u32_e32 vcc, v5, v4
	s_nop 1
	v_cndmask_b32_e32 v3, v3, v6, vcc
	v_sub_u32_e32 v6, v5, v4
	v_cndmask_b32_e32 v5, v5, v6, vcc
	v_add_u32_e32 v6, 1, v3
	v_cmp_ge_u32_e32 vcc, v5, v4
	v_add_u32_e32 v5, 1, v7
	s_nop 0
	v_cndmask_b32_e32 v3, v3, v6, vcc
	v_mul_lo_u32 v6, v4, v3
	v_add_u32_e32 v4, v6, v4
	v_cmp_ne_u32_e32 vcc, v5, v4
	s_cbranch_vccnz .Lsm5_poll
	buffer_wbl2 sc1
	s_waitcnt vmcnt(0) lgkmcnt(0)
	v_mov_b32_e32 v5, 0x1e03000
	v_mov_b32_e32 v6, 1
	global_atomic_add v5, v6, s[40:41] offset:1024

.Lsm5_done:
	buffer_inv sc1
	s_waitcnt vmcnt(0)
.LBB0_898:
	s_or_b64 exec, exec, s[0:1]
	s_waitcnt lgkmcnt(0)
	s_barrier

.LBB0_1082:
	s_or_b64 exec, exec, s[6:7]
	v_cvt_f32_u32_e32 v4, v2
	s_waitcnt vmcnt(0)
	v_readfirstlane_b32 s6, v3
	v_sub_u32_e32 v3, 0, v2
	v_rcp_iflag_f32_e32 v4, v4
	v_add_u32_e32 v5, s6, v1
	v_mul_f32_e32 v4, 0x4f7ffffe, v4
	v_cvt_u32_f32_e32 v4, v4
	v_mul_lo_u32 v1, v3, v4
	v_mul_hi_u32 v1, v4, v1
	v_add_u32_e32 v1, v4, v1
	v_mul_hi_u32 v1, v5, v1
	v_mul_lo_u32 v3, v1, v2
	v_sub_u32_e32 v3, v5, v3
	v_add_u32_e32 v4, 1, v1
	v_cmp_ge_u32_e32 vcc, v3, v2
	s_nop 1
	v_cndmask_b32_e32 v1, v1, v4, vcc
	v_sub_u32_e32 v4, v3, v2
	v_cndmask_b32_e32 v3, v3, v4, vcc
	v_add_u32_e32 v4, 1, v1
	v_cmp_ge_u32_e32 vcc, v3, v2
	v_add_u32_e32 v3, 1, v5
	s_nop 0
	v_cndmask_b32_e32 v1, v1, v4, vcc
	v_mul_lo_u32 v4, v2, v1
	v_add_u32_e32 v2, v4, v2
	v_cmp_ne_u32_e32 vcc, v3, v2
	s_cbranch_vccnz .Lsm6_poll
	buffer_wbl2 sc1
	s_waitcnt vmcnt(0) lgkmcnt(0)
	v_readlane_b32 s98, v253, 43
	v_readlane_b32 s99, v253, 44
	v_mov_b32_e32 v4, 1
	s_nop 4
	global_atomic_add v139, v4, s[98:99]
.Lsm6_poll:
	s_waitcnt lgkmcnt(0)
	v_readlane_b32 s98, v253, 43
	v_readlane_b32 s99, v253, 44
	v_add_u32_e32 v4, 1, v1
	v_mul_lo_u32 v4, v4, v0
	s_mov_b32 s101, 0x800
	s_nop 4
.Lsm6_loop:
	global_load_dword v3, v139, s[98:99] sc1
	s_waitcnt vmcnt(0)
	v_cmp_ge_u32_e32 vcc, v3, v4
	s_cbranch_vccnz .Lsm6_done
	s_sleep 1
	s_add_i32 s101, s101, -1
	s_cmp_lg_u32 s101, 0
	s_cbranch_scc1 .Lsm6_loop
.Lsm6_done:
	buffer_inv sc1
	s_waitcnt vmcnt(0)
.LBB0_1116:
	s_or_b64 exec, exec, s[0:1]
	s_waitcnt lgkmcnt(0)
	s_barrier

.LBB0_1461:
	s_or_b64 exec, exec, s[4:5]
	v_cvt_f32_u32_e32 v4, v2
	s_waitcnt vmcnt(0)
	v_readfirstlane_b32 s4, v3
	v_sub_u32_e32 v3, 0, v2
	v_rcp_iflag_f32_e32 v4, v4
	v_add_u32_e32 v5, s4, v1
	v_mul_f32_e32 v4, 0x4f7ffffe, v4
	v_cvt_u32_f32_e32 v4, v4
	v_mul_lo_u32 v1, v3, v4
	v_mul_hi_u32 v1, v4, v1
	v_add_u32_e32 v1, v4, v1
	v_mul_hi_u32 v1, v5, v1
	v_mul_lo_u32 v3, v1, v2
	v_sub_u32_e32 v3, v5, v3
	v_add_u32_e32 v4, 1, v1
	v_cmp_ge_u32_e32 vcc, v3, v2
	s_nop 1
	v_cndmask_b32_e32 v1, v1, v4, vcc
	v_sub_u32_e32 v4, v3, v2
	v_cndmask_b32_e32 v3, v3, v4, vcc
	v_add_u32_e32 v4, 1, v1
	v_cmp_ge_u32_e32 vcc, v3, v2
	v_add_u32_e32 v3, 1, v5
	s_nop 0
	v_cndmask_b32_e32 v1, v1, v4, vcc
	v_mul_lo_u32 v4, v2, v1
	v_add_u32_e32 v2, v4, v2
	v_cmp_ne_u32_e32 vcc, v3, v2
	s_cbranch_vccnz .Lsm7_poll
	buffer_wbl2 sc1
	s_waitcnt vmcnt(0) lgkmcnt(0)
	v_readlane_b32 s98, v253, 43
	v_readlane_b32 s99, v253, 44
	v_mov_b32_e32 v4, 1
	s_nop 4
	global_atomic_add v139, v4, s[98:99]

.Lsm7_done:
	buffer_inv sc1
	s_waitcnt vmcnt(0)
	s_branch .LBB0_901
